# P0 step 1 (weight transposes) rewritten by hand: scalar addressing, next tile's loads prefetched, double-buffered LDS tile with one barrier, packed 4-byte stores
# speedup vs baseline: 1.0022x; 1.0022x over previous
; __device__ __forceinline__ void p0_prologue(const Params& p, LAS unsigned char* lds, const int wave_s) {
;     ...
;     for (int t = blockIdx.x; t < 2752; t += G) {
;         const float* src; int ld, k0, n0, kind;
;         if (t < 512) { kind = 0; k0 = (t >> 5) * 64; n0 = (t & 31) * 64; src = p.in[I_WIN]; ld = 2048; }
;         else if (t < 640) { const int u = t - 512; kind = 1; k0 = (u >> 4) * 64; n0 = (u & 15) * 64; src = p.in[I_WOUT]; ld = 1024; }
;         else if (t < 2048) { const int u = t - 640; kind = 2; k0 = (u / 88) * 64; n0 = (u % 88) * 64; src = p.in[I_WUP]; ld = 5632; }
;         else { const int u = t - 2048; kind = 3; k0 = (u >> 4) * 64; n0 = (u & 15) * 64; src = p.in[I_WDOWN]; ld = 1024; }
; #pragma unroll
;         for (int i = 0; i < 8; ++i) { const int e = tid + i * 512, kk = e >> 6, nn = e & 63;
;             float v = src[(size_t)(k0 + kk) * ld + n0 + nn];
;             if (kind == 1) v *= p.in[I_SUBG][(k0 + kk) & 127] * 0.8f;
;             if (kind == 2) v *= p.in[I_N2G][k0 + kk];
;             tile[kk * 65 + nn] = v; }
.LBB0_5:
	s_or_b64 exec, exec, s[2:3]
	s_load_dwordx16 s[36:51], s[0:1], 0x0
	s_and_b32 s90, s33, 0xffffffc0
	v_mbcnt_lo_u32_b32 v1, -1, 0
	v_mbcnt_hi_u32_b32 v1, -1, v1
	s_add_u32 s18, s80, 0x400000
	v_add_u32_e32 v1, s90, v1
	s_addc_u32 s19, s81, 0
	s_cmpk_gt_i32 s93, 0xabf
	v_and_b32_e32 v42, 63, v1
	v_ashrrev_i32_e32 v53, 6, v1
	s_cbranch_scc1 .LBB0_180
	s_waitcnt lgkmcnt(0)
	v_readlane_b32 s34, v255, 4
	v_readlane_b32 s35, v255, 5
	s_lshr_b32 s20, s90, 6
	s_lshl_b32 s21, s20, 1
	v_lshlrev_b32_e32 v2, 2, v42
	v_mov_b32_e32 v3, 0
	s_movk_i32 s0, 0x104
	v_mad_u32_u24 v36, v53, s0, v2
	v_and_b32_e32 v39, 31, v42
	v_lshrrev_b32_e32 v40, 5, v42
	s_movk_i32 s1, 0x208
	v_mul_u32_u24_e32 v37, s1, v39
	v_lshl_add_u32 v37, v40, 2, v37
	v_lshl_add_u32 v37, v53, 3, v37
	v_lshlrev_b32_e32 v41, 2, v39
	s_mov_b32 s52, s93
	s_cmpk_lt_u32 s52, 0x200
	s_cbranch_scc1 .Lp0t_k0_1
	s_cmpk_lt_u32 s52, 0x280
	s_cbranch_scc1 .Lp0t_k1_2
	s_cmpk_lt_u32 s52, 0x800
	s_cbranch_scc1 .Lp0t_k2_3
	s_add_i32 s0, s52, 0xfffff800
	s_lshr_b32 s1, s0, 4
	s_lshl_b32 s1, s1, 6
	s_and_b32 s2, s0, 15
	s_lshl_b32 s2, s2, 6
	s_mov_b64 s[4:5], s[34:35]
	s_movk_i32 s15, 0x1000
	s_mov_b32 s22, 0
	s_mov_b64 s[8:9], s[60:61]
	s_lshl_b32 s10, s20, 2
	s_mul_i32 s11, s2, 0x1600
	s_lshl_b32 s12, s1, 1
	s_add_i32 s11, s11, s12
	s_add_i32 s11, s11, 0x1100000
	s_movk_i32 s26, 0x1600
	s_mov_b32 s27, 0x16000
	s_branch .Lp0t_cm_4
.Lp0t_k0_1:
	s_lshr_b32 s1, s52, 5
	s_lshl_b32 s1, s1, 6
	s_and_b32 s2, s52, 31
	s_lshl_b32 s2, s2, 6
	s_mov_b64 s[4:5], s[42:43]
	s_movk_i32 s15, 0x2000
	s_mov_b32 s22, 0
	s_mov_b64 s[8:9], s[60:61]
	s_lshl_b32 s10, s20, 2
	s_movk_i32 s26, 0x800
	s_mov_b32 s0, s2
	s_cmpk_lt_u32 s2, 0x400
	s_cbranch_scc1 .Lp0t_pm_6
	s_cmpk_lt_u32 s2, 0x600
	s_cbranch_scc1 .Lp0t_wv_5
	s_add_i32 s0, s2, 0xfffffe00
.Lp0t_pm_6:
	s_and_b32 s11, s0, 0xffffff00
	s_bfe_u32 s12, s0, 0x20006
	s_lshl_b32 s12, s12, 5
	s_add_i32 s11, s11, s12
	s_lshl_b32 s11, s11, 11
	s_lshl_b32 s12, s1, 1
	s_add_i32 s11, s11, s12
	s_mov_b32 s27, 0x38000
	s_branch .Lp0t_cm_4
.Lp0t_wv_5:
	s_add_i32 s11, s2, 0xfffffc00
	s_lshl_b32 s11, s11, 11
	s_lshl_b32 s12, s1, 1
	s_add_i32 s11, s11, s12
	s_add_i32 s11, s11, 0x300000
	s_mov_b32 s27, 0x8000
	s_branch .Lp0t_cm_4
.Lp0t_k1_2:
	s_add_i32 s0, s52, 0xfffffe00
	s_lshr_b32 s1, s0, 4
	s_lshl_b32 s1, s1, 6
	s_and_b32 s2, s0, 15
	s_lshl_b32 s2, s2, 6
	s_mov_b64 s[4:5], s[66:67]
	s_movk_i32 s15, 0x1000
	s_mov_b32 s22, 1
	s_mov_b64 s[8:9], s[60:61]
	s_and_b32 s10, s1, 64
	s_add_i32 s10, s10, s20
	s_lshl_b32 s10, s10, 2
	s_lshl_b32 s11, s2, 11
	s_lshl_b32 s12, s1, 1
	s_add_i32 s11, s11, s12
	s_add_i32 s11, s11, 0x400000
	s_movk_i32 s26, 0x800
	s_mov_b32 s27, 0x8000
	s_branch .Lp0t_cm_4
.Lp0t_k2_3:
	s_add_i32 s0, s52, 0xfffffd80
	s_and_b32 s1, s0, 0xffff
	s_mul_i32 s1, s1, 0xba2f
	s_lshr_b32 s1, s1, 22
	s_mul_i32 s2, s1, 88
	s_sub_i32 s2, s0, s2
	s_lshl_b32 s1, s1, 6
	s_lshl_b32 s2, s2, 6
	s_mov_b64 s[4:5], s[70:71]
	s_movk_i32 s15, 0x5800
	s_mov_b32 s22, 2
	s_mov_b64 s[8:9], s[68:69]
	s_add_i32 s10, s1, s20
	s_lshl_b32 s10, s10, 2
	s_cmpk_lt_u32 s2, 0xb00
	s_cselect_b32 s12, 0, 0xb00
	s_cselect_b32 s13, 0, 0x80
	s_sub_i32 s0, s2, s12
	s_lshr_b32 s11, s0, 7
	s_lshl_b32 s11, s11, 8
	s_add_i32 s11, s11, s13
	s_and_b32 s12, s0, 64
	s_add_i32 s11, s11, s12
	s_lshl_b32 s11, s11, 11
	s_lshl_b32 s12, s1, 1
	s_add_i32 s11, s11, s12
	s_add_i32 s11, s11, 0x600000
	s_movk_i32 s26, 0x800
	s_mov_b32 s27, 0x8000
.Lp0t_cm_4:
	s_add_i32 s13, s1, s20
	s_mul_i32 s13, s13, s15
	s_lshl_b32 s14, s2, 2
	s_add_i32 s13, s13, s14
	s_add_u32 s4, s4, s13
	s_addc_u32 s5, s5, 0
	s_lshl_b32 s15, s15, 3
	s_add_u32 s8, s8, s10
	s_addc_u32 s9, s9, 0
	s_add_u32 s24, s80, s11
	s_addc_u32 s25, s81, 0
	global_load_dword v4, v2, s[4:5]
	s_add_u32 s4, s4, s15
	s_addc_u32 s5, s5, 0
	global_load_dword v5, v2, s[4:5]
	s_add_u32 s4, s4, s15
	s_addc_u32 s5, s5, 0
	global_load_dword v6, v2, s[4:5]
	s_add_u32 s4, s4, s15
	s_addc_u32 s5, s5, 0
	global_load_dword v7, v2, s[4:5]
	s_add_u32 s4, s4, s15
	s_addc_u32 s5, s5, 0
	global_load_dword v8, v2, s[4:5]
	s_add_u32 s4, s4, s15
	s_addc_u32 s5, s5, 0
	global_load_dword v9, v2, s[4:5]
	s_add_u32 s4, s4, s15
	s_addc_u32 s5, s5, 0
	global_load_dword v10, v2, s[4:5]
	s_add_u32 s4, s4, s15
	s_addc_u32 s5, s5, 0
	global_load_dword v11, v2, s[4:5]
	global_load_dword v20, v3, s[8:9]
	global_load_dword v21, v3, s[8:9] offset:32
	global_load_dword v22, v3, s[8:9] offset:64
	global_load_dword v23, v3, s[8:9] offset:96
	global_load_dword v24, v3, s[8:9] offset:128
	global_load_dword v25, v3, s[8:9] offset:160
	global_load_dword v26, v3, s[8:9] offset:192
	global_load_dword v27, v3, s[8:9] offset:224
	s_mov_b32 s28, s22
	s_mov_b64 s[30:31], s[24:25]
	s_mov_b32 s32, s26
	s_mov_b32 s29, s27
.Lp0t_half_a:
	s_add_i32 s53, s52, s82
	s_cmpk_gt_u32 s53, 0xabf
	s_cbranch_scc1 .Lp0t_nonext_7
	s_cmpk_lt_u32 s53, 0x200
	s_cbranch_scc1 .Lp0t_k0_9
	s_cmpk_lt_u32 s53, 0x280
	s_cbranch_scc1 .Lp0t_k1_10
	s_cmpk_lt_u32 s53, 0x800
	s_cbranch_scc1 .Lp0t_k2_11
	s_add_i32 s0, s53, 0xfffff800
	s_lshr_b32 s1, s0, 4
	s_lshl_b32 s1, s1, 6
	s_and_b32 s2, s0, 15
	s_lshl_b32 s2, s2, 6
	s_mov_b64 s[4:5], s[34:35]
	s_movk_i32 s15, 0x1000
	s_mov_b32 s22, 0
	s_mov_b64 s[8:9], s[60:61]
	s_lshl_b32 s10, s20, 2
	s_mul_i32 s11, s2, 0x1600
	s_lshl_b32 s12, s1, 1
	s_add_i32 s11, s11, s12
	s_add_i32 s11, s11, 0x1100000
	s_movk_i32 s26, 0x1600
	s_mov_b32 s27, 0x16000
	s_branch .Lp0t_cm_12
.Lp0t_k0_9:
	s_lshr_b32 s1, s53, 5
	s_lshl_b32 s1, s1, 6
	s_and_b32 s2, s53, 31
	s_lshl_b32 s2, s2, 6
	s_mov_b64 s[4:5], s[42:43]
	s_movk_i32 s15, 0x2000
	s_mov_b32 s22, 0
	s_mov_b64 s[8:9], s[60:61]
	s_lshl_b32 s10, s20, 2
	s_movk_i32 s26, 0x800
	s_mov_b32 s0, s2
	s_cmpk_lt_u32 s2, 0x400
	s_cbranch_scc1 .Lp0t_pm_14
	s_cmpk_lt_u32 s2, 0x600
	s_cbranch_scc1 .Lp0t_wv_13
	s_add_i32 s0, s2, 0xfffffe00

; __device__ __forceinline__ void p0_prologue(const Params& p, LAS unsigned char* lds, const int wave_s) {
;     ...
;         if (t < 512) { kind = 0; k0 = (t >> 5) * 64; n0 = (t & 31) * 64; src = p.in[I_WIN]; ld = 2048; }
;         else if (t < 640) { const int u = t - 512; kind = 1; k0 = (u >> 4) * 64; n0 = (u & 15) * 64; src = p.in[I_WOUT]; ld = 1024; }
;         else if (t < 2048) { const int u = t - 640; kind = 2; k0 = (u / 88) * 64; n0 = (u % 88) * 64; src = p.in[I_WUP]; ld = 5632; }
;         else { const int u = t - 2048; kind = 3; k0 = (u >> 4) * 64; n0 = (u & 15) * 64; src = p.in[I_WDOWN]; ld = 1024; }
; #pragma unroll
;         for (int i = 0; i < 8; ++i) { const int e = tid + i * 512, kk = e >> 6, nn = e & 63;
;             float v = src[(size_t)(k0 + kk) * ld + n0 + nn];
;             if (kind == 1) v *= p.in[I_SUBG][(k0 + kk) & 127] * 0.8f;
;             if (kind == 2) v *= p.in[I_N2G][k0 + kk];
;             tile[kk * 65 + nn] = v; }
.Lp0t_k1_10:
	s_add_i32 s0, s53, 0xfffffe00
	s_lshr_b32 s1, s0, 4
	s_lshl_b32 s1, s1, 6
	s_and_b32 s2, s0, 15
	s_lshl_b32 s2, s2, 6
	s_mov_b64 s[4:5], s[66:67]
	s_movk_i32 s15, 0x1000
	s_mov_b32 s22, 1
	s_mov_b64 s[8:9], s[60:61]
	s_and_b32 s10, s1, 64
	s_add_i32 s10, s10, s20
	s_lshl_b32 s10, s10, 2
	s_lshl_b32 s11, s2, 11
	s_lshl_b32 s12, s1, 1
	s_add_i32 s11, s11, s12
	s_add_i32 s11, s11, 0x400000
	s_movk_i32 s26, 0x800
	s_mov_b32 s27, 0x8000
	s_branch .Lp0t_cm_12
.Lp0t_k2_11:
	s_add_i32 s0, s53, 0xfffffd80
	s_and_b32 s1, s0, 0xffff
	s_mul_i32 s1, s1, 0xba2f
	s_lshr_b32 s1, s1, 22
	s_mul_i32 s2, s1, 88
	s_sub_i32 s2, s0, s2
	s_lshl_b32 s1, s1, 6
	s_lshl_b32 s2, s2, 6
	s_mov_b64 s[4:5], s[70:71]
	s_movk_i32 s15, 0x5800
	s_mov_b32 s22, 2
	s_mov_b64 s[8:9], s[68:69]
	s_add_i32 s10, s1, s20
	s_lshl_b32 s10, s10, 2
	s_cmpk_lt_u32 s2, 0xb00
	s_cselect_b32 s12, 0, 0xb00
	s_cselect_b32 s13, 0, 0x80
	s_sub_i32 s0, s2, s12
	s_lshr_b32 s11, s0, 7
	s_lshl_b32 s11, s11, 8
	s_add_i32 s11, s11, s13
	s_and_b32 s12, s0, 64
	s_add_i32 s11, s11, s12
	s_lshl_b32 s11, s11, 11
	s_lshl_b32 s12, s1, 1
	s_add_i32 s11, s11, s12
	s_add_i32 s11, s11, 0x600000
	s_movk_i32 s26, 0x800
	s_mov_b32 s27, 0x8000
.Lp0t_cm_12:
	s_add_i32 s13, s1, s20
	s_mul_i32 s13, s13, s15
	s_lshl_b32 s14, s2, 2
	s_add_i32 s13, s13, s14
	s_add_u32 s4, s4, s13
	s_addc_u32 s5, s5, 0
	s_lshl_b32 s15, s15, 3
	s_add_u32 s8, s8, s10
	s_addc_u32 s9, s9, 0
	s_add_u32 s24, s80, s11
	s_addc_u32 s25, s81, 0
	global_load_dword v12, v2, s[4:5]
	s_add_u32 s4, s4, s15
	s_addc_u32 s5, s5, 0
	global_load_dword v13, v2, s[4:5]
	s_add_u32 s4, s4, s15
	s_addc_u32 s5, s5, 0
	global_load_dword v14, v2, s[4:5]
	s_add_u32 s4, s4, s15
	s_addc_u32 s5, s5, 0
	global_load_dword v15, v2, s[4:5]
	s_add_u32 s4, s4, s15
	s_addc_u32 s5, s5, 0
	global_load_dword v16, v2, s[4:5]
	s_add_u32 s4, s4, s15
	s_addc_u32 s5, s5, 0
	global_load_dword v17, v2, s[4:5]
	s_add_u32 s4, s4, s15
	s_addc_u32 s5, s5, 0
	global_load_dword v18, v2, s[4:5]
	s_add_u32 s4, s4, s15
	s_addc_u32 s5, s5, 0
	global_load_dword v19, v2, s[4:5]
	global_load_dword v28, v3, s[8:9]
	global_load_dword v29, v3, s[8:9] offset:32
	global_load_dword v30, v3, s[8:9] offset:64
	global_load_dword v31, v3, s[8:9] offset:96
	global_load_dword v32, v3, s[8:9] offset:128
	global_load_dword v33, v3, s[8:9] offset:160
	global_load_dword v34, v3, s[8:9] offset:192
	global_load_dword v35, v3, s[8:9] offset:224
	s_waitcnt vmcnt(16)
	s_branch .Lp0t_proc_8

; __device__ __forceinline__ bf16_t f2bf(float x) { unsigned u = __float_as_uint(x); u += 0x7fffu + ((u >> 16) & 1u); return (bf16_t)(u >> 16); }
; __device__ __forceinline__ void p0_prologue(const Params& p, LAS unsigned char* lds, const int wave_s) {
;     ...
;         for (int i = 0; i < 8; ++i) { const int e = tid + i * 512, kk = e >> 6, nn = e & 63;
;             float v = src[(size_t)(k0 + kk) * ld + n0 + nn];
;             if (kind == 1) v *= p.in[I_SUBG][(k0 + kk) & 127] * 0.8f;
;             if (kind == 2) v *= p.in[I_N2G][k0 + kk];
;             tile[kk * 65 + nn] = v; }
;         __syncthreads();
; #pragma unroll
;         for (int i = 0; i < 8; ++i) { const int e = tid + i * 512, nn = e >> 6, kk = e & 63, n = n0 + nn; bf16_t* dst;
;             if (kind == 0) {
;                 if (n < 1024 || n >= 1536) { const int L = n < 1024 ? n : n - 512; const int prow = (L & ~255) + ((L >> 5) & 1) * 128 + ((L >> 6) & 3) * 32 + (L & 31); dst = WQKP + (size_t)prow * 1024 + k0 + kk; }
;                 else dst = WV + (size_t)(n - 1024) * 1024 + k0 + kk;
;             } else if (kind == 1) dst = WOUT + (size_t)n * 1024 + k0 + kk;
;             else if (kind == 2) { const int f = n < DFF ? n : n - DFF; const int prow = (f >> 7) * 256 + (n < DFF ? 0 : 128) + (f & 127); dst = WUP + (size_t)prow * 1024 + k0 + kk; }
;             else dst = WDN + (size_t)n * DFF + k0 + kk;
;             *dst = f2bf(tile[kk * 65 + nn]); }
;         __syncthreads();
.Lp0t_proc_8:
	s_cmp_eq_u32 s28, 0
	s_cbranch_scc1 .Lp0t_nosc_15
	s_cmp_eq_u32 s28, 2
	s_cbranch_scc1 .Lp0t_sc2_16
	v_mul_f32_e32 v20, 0x3f4ccccd, v20
	v_mul_f32_e32 v21, 0x3f4ccccd, v21
	v_mul_f32_e32 v22, 0x3f4ccccd, v22
	v_mul_f32_e32 v23, 0x3f4ccccd, v23
	v_mul_f32_e32 v24, 0x3f4ccccd, v24
	v_mul_f32_e32 v25, 0x3f4ccccd, v25
	v_mul_f32_e32 v26, 0x3f4ccccd, v26
	v_mul_f32_e32 v27, 0x3f4ccccd, v27
.Lp0t_sc2_16:
	v_mul_f32_e32 v4, v4, v20
	v_mul_f32_e32 v5, v5, v21
	v_mul_f32_e32 v6, v6, v22
	v_mul_f32_e32 v7, v7, v23
	v_mul_f32_e32 v8, v8, v24
	v_mul_f32_e32 v9, v9, v25
	v_mul_f32_e32 v10, v10, v26
	v_mul_f32_e32 v11, v11, v27
.Lp0t_nosc_15:
	ds_write_b32 v36, v4
	ds_write_b32 v36, v5 offset:2080
	ds_write_b32 v36, v6 offset:4160
	ds_write_b32 v36, v7 offset:6240
	ds_write_b32 v36, v8 offset:8320
	ds_write_b32 v36, v9 offset:10400
	ds_write_b32 v36, v10 offset:12480
	ds_write_b32 v36, v11 offset:14560
	s_mul_i32 s0, s32, s21
	s_add_u32 s0, s30, s0
	s_addc_u32 s1, s31, 0
	s_lshl_b32 s2, s32, 4
	v_mad_u32_u24 v38, v40, s32, v41
	s_waitcnt lgkmcnt(0)
	s_barrier
	ds_read2_b32 v[44:45], v37 offset0:0 offset1:65
	ds_read2_b32 v[46:47], v37 offset0:16 offset1:81
	ds_read2_b32 v[48:49], v37 offset0:32 offset1:97
	ds_read2_b32 v[50:51], v37 offset0:48 offset1:113
	v_xor_b32_e32 v36, 0x8000, v36
	s_waitcnt lgkmcnt(3)
	v_cvt_pk_bf16_f32 v44, v44, v45
	global_store_dword v38, v44, s[0:1]
	s_add_u32 s0, s0, s2
	s_addc_u32 s1, s1, 0
	s_waitcnt lgkmcnt(2)
	v_cvt_pk_bf16_f32 v46, v46, v47
	global_store_dword v38, v46, s[0:1]
	s_add_u32 s0, s0, s29
	s_addc_u32 s1, s1, 0
	s_waitcnt lgkmcnt(1)
	v_cvt_pk_bf16_f32 v48, v48, v49
	global_store_dword v38, v48, s[0:1]
	s_add_u32 s0, s0, s2
	s_addc_u32 s1, s1, 0
	s_waitcnt lgkmcnt(0)
	v_cvt_pk_bf16_f32 v50, v50, v51
	global_store_dword v38, v50, s[0:1]
	v_xor_b32_e32 v37, 0x8000, v37
	s_cmpk_gt_u32 s53, 0xabf
	s_cbranch_scc1 .Lp0t_done
	s_mov_b32 s28, s22
	s_mov_b64 s[30:31], s[24:25]
	s_mov_b32 s32, s26
	s_mov_b32 s29, s27
	s_mov_b32 s52, s53
	s_add_i32 s53, s52, s82
	s_cmpk_gt_u32 s53, 0xabf
	s_cbranch_scc1 .Lp0t_nonext_17
	s_cmpk_lt_u32 s53, 0x200
	s_cbranch_scc1 .Lp0t_k0_19
	s_cmpk_lt_u32 s53, 0x280
	s_cbranch_scc1 .Lp0t_k1_20
	s_cmpk_lt_u32 s53, 0x800
	s_cbranch_scc1 .Lp0t_k2_21
	s_add_i32 s0, s53, 0xfffff800
	s_lshr_b32 s1, s0, 4
	s_lshl_b32 s1, s1, 6
	s_and_b32 s2, s0, 15
	s_lshl_b32 s2, s2, 6
	s_mov_b64 s[4:5], s[34:35]
	s_movk_i32 s15, 0x1000
	s_mov_b32 s22, 0
	s_mov_b64 s[8:9], s[60:61]
	s_lshl_b32 s10, s20, 2
	s_mul_i32 s11, s2, 0x1600
	s_lshl_b32 s12, s1, 1
	s_add_i32 s11, s11, s12
	s_add_i32 s11, s11, 0x1100000
	s_movk_i32 s26, 0x1600
	s_mov_b32 s27, 0x16000
	s_branch .Lp0t_cm_22

; __device__ __forceinline__ void p0_prologue(const Params& p, LAS unsigned char* lds, const int wave_s) {
;     ...
;     for (int t = blockIdx.x; t < 2752; t += G) {
;         const float* src; int ld, k0, n0, kind;
;         if (t < 512) { kind = 0; k0 = (t >> 5) * 64; n0 = (t & 31) * 64; src = p.in[I_WIN]; ld = 2048; }
;         else if (t < 640) { const int u = t - 512; kind = 1; k0 = (u >> 4) * 64; n0 = (u & 15) * 64; src = p.in[I_WOUT]; ld = 1024; }
;         else if (t < 2048) { const int u = t - 640; kind = 2; k0 = (u / 88) * 64; n0 = (u % 88) * 64; src = p.in[I_WUP]; ld = 5632; }
;         else { const int u = t - 2048; kind = 3; k0 = (u >> 4) * 64; n0 = (u & 15) * 64; src = p.in[I_WDOWN]; ld = 1024; }
; #pragma unroll
;         for (int i = 0; i < 8; ++i) { const int e = tid + i * 512, kk = e >> 6, nn = e & 63;
;             float v = src[(size_t)(k0 + kk) * ld + n0 + nn];
;             if (kind == 1) v *= p.in[I_SUBG][(k0 + kk) & 127] * 0.8f;
;             if (kind == 2) v *= p.in[I_N2G][k0 + kk];
;             tile[kk * 65 + nn] = v; }
.Lp0t_cm_22:
	s_add_i32 s13, s1, s20
	s_mul_i32 s13, s13, s15
	s_lshl_b32 s14, s2, 2
	s_add_i32 s13, s13, s14
	s_add_u32 s4, s4, s13
	s_addc_u32 s5, s5, 0
	s_lshl_b32 s15, s15, 3
	s_add_u32 s8, s8, s10
	s_addc_u32 s9, s9, 0
	s_add_u32 s24, s80, s11
	s_addc_u32 s25, s81, 0
	global_load_dword v4, v2, s[4:5]
	s_add_u32 s4, s4, s15
	s_addc_u32 s5, s5, 0
	global_load_dword v5, v2, s[4:5]
	s_add_u32 s4, s4, s15
	s_addc_u32 s5, s5, 0
	global_load_dword v6, v2, s[4:5]
	s_add_u32 s4, s4, s15
	s_addc_u32 s5, s5, 0
	global_load_dword v7, v2, s[4:5]
	s_add_u32 s4, s4, s15
	s_addc_u32 s5, s5, 0
	global_load_dword v8, v2, s[4:5]
	s_add_u32 s4, s4, s15
	s_addc_u32 s5, s5, 0
	global_load_dword v9, v2, s[4:5]
	s_add_u32 s4, s4, s15
	s_addc_u32 s5, s5, 0
	global_load_dword v10, v2, s[4:5]
	s_add_u32 s4, s4, s15
	s_addc_u32 s5, s5, 0
	global_load_dword v11, v2, s[4:5]
	global_load_dword v20, v3, s[8:9]
	global_load_dword v21, v3, s[8:9] offset:32
	global_load_dword v22, v3, s[8:9] offset:64
	global_load_dword v23, v3, s[8:9] offset:96
	global_load_dword v24, v3, s[8:9] offset:128
	global_load_dword v25, v3, s[8:9] offset:160
	global_load_dword v26, v3, s[8:9] offset:192
	global_load_dword v27, v3, s[8:9] offset:224
	s_waitcnt vmcnt(16)
	s_branch .Lp0t_proc_18

; __device__ __forceinline__ bf16_t f2bf(float x) { unsigned u = __float_as_uint(x); u += 0x7fffu + ((u >> 16) & 1u); return (bf16_t)(u >> 16); }
; __device__ __forceinline__ void p0_prologue(const Params& p, LAS unsigned char* lds, const int wave_s) {
;     ...
;         for (int i = 0; i < 8; ++i) { const int e = tid + i * 512, kk = e >> 6, nn = e & 63;
;             float v = src[(size_t)(k0 + kk) * ld + n0 + nn];
;             if (kind == 1) v *= p.in[I_SUBG][(k0 + kk) & 127] * 0.8f;
;             if (kind == 2) v *= p.in[I_N2G][k0 + kk];
;             tile[kk * 65 + nn] = v; }
;         __syncthreads();
; #pragma unroll
;         for (int i = 0; i < 8; ++i) { const int e = tid + i * 512, nn = e >> 6, kk = e & 63, n = n0 + nn; bf16_t* dst;
;             if (kind == 0) {
;                 if (n < 1024 || n >= 1536) { const int L = n < 1024 ? n : n - 512; const int prow = (L & ~255) + ((L >> 5) & 1) * 128 + ((L >> 6) & 3) * 32 + (L & 31); dst = WQKP + (size_t)prow * 1024 + k0 + kk; }
;                 else dst = WV + (size_t)(n - 1024) * 1024 + k0 + kk;
;             } else if (kind == 1) dst = WOUT + (size_t)n * 1024 + k0 + kk;
;             else if (kind == 2) { const int f = n < DFF ? n : n - DFF; const int prow = (f >> 7) * 256 + (n < DFF ? 0 : 128) + (f & 127); dst = WUP + (size_t)prow * 1024 + k0 + kk; }
;             else dst = WDN + (size_t)n * DFF + k0 + kk;
;             *dst = f2bf(tile[kk * 65 + nn]); }
;         __syncthreads();
;     }
.Lp0t_proc_18:
	s_cmp_eq_u32 s28, 0
	s_cbranch_scc1 .Lp0t_nosc_25
	s_cmp_eq_u32 s28, 2
	s_cbranch_scc1 .Lp0t_sc2_26
	v_mul_f32_e32 v28, 0x3f4ccccd, v28
	v_mul_f32_e32 v29, 0x3f4ccccd, v29
	v_mul_f32_e32 v30, 0x3f4ccccd, v30
	v_mul_f32_e32 v31, 0x3f4ccccd, v31
	v_mul_f32_e32 v32, 0x3f4ccccd, v32
	v_mul_f32_e32 v33, 0x3f4ccccd, v33
	v_mul_f32_e32 v34, 0x3f4ccccd, v34
	v_mul_f32_e32 v35, 0x3f4ccccd, v35
.Lp0t_sc2_26:
	v_mul_f32_e32 v12, v12, v28
	v_mul_f32_e32 v13, v13, v29
	v_mul_f32_e32 v14, v14, v30
	v_mul_f32_e32 v15, v15, v31
	v_mul_f32_e32 v16, v16, v32
	v_mul_f32_e32 v17, v17, v33
	v_mul_f32_e32 v18, v18, v34
	v_mul_f32_e32 v19, v19, v35
.Lp0t_nosc_25:
	ds_write_b32 v36, v12
	ds_write_b32 v36, v13 offset:2080
	ds_write_b32 v36, v14 offset:4160
	ds_write_b32 v36, v15 offset:6240
	ds_write_b32 v36, v16 offset:8320
	ds_write_b32 v36, v17 offset:10400
	ds_write_b32 v36, v18 offset:12480
	ds_write_b32 v36, v19 offset:14560
	s_mul_i32 s0, s32, s21
	s_add_u32 s0, s30, s0
	s_addc_u32 s1, s31, 0
	s_lshl_b32 s2, s32, 4
	v_mad_u32_u24 v38, v40, s32, v41
	s_waitcnt lgkmcnt(0)
	s_barrier
	ds_read2_b32 v[44:45], v37 offset0:0 offset1:65
	ds_read2_b32 v[46:47], v37 offset0:16 offset1:81
	ds_read2_b32 v[48:49], v37 offset0:32 offset1:97
	ds_read2_b32 v[50:51], v37 offset0:48 offset1:113
	v_xor_b32_e32 v36, 0x8000, v36
	s_waitcnt lgkmcnt(3)
	v_cvt_pk_bf16_f32 v44, v44, v45
	global_store_dword v38, v44, s[0:1]
	s_add_u32 s0, s0, s2
	s_addc_u32 s1, s1, 0
	s_waitcnt lgkmcnt(2)
	v_cvt_pk_bf16_f32 v46, v46, v47
	global_store_dword v38, v46, s[0:1]
	s_add_u32 s0, s0, s29
	s_addc_u32 s1, s1, 0
	s_waitcnt lgkmcnt(1)
	v_cvt_pk_bf16_f32 v48, v48, v49
	global_store_dword v38, v48, s[0:1]
	s_add_u32 s0, s0, s2
	s_addc_u32 s1, s1, 0
	s_waitcnt lgkmcnt(0)
	v_cvt_pk_bf16_f32 v50, v50, v51
	global_store_dword v38, v50, s[0:1]
	v_xor_b32_e32 v37, 0x8000, v37
	s_cmpk_gt_u32 s53, 0xabf
	s_cbranch_scc1 .Lp0t_done
	s_mov_b32 s28, s22
	s_mov_b64 s[30:31], s[24:25]
	s_mov_b32 s32, s26
	s_mov_b32 s29, s27
	s_mov_b32 s52, s53
	s_branch .Lp0t_half_a
.Lp0t_done:
.LBB0_180:
	s_lshl_b32 s70, s93, 9
	v_add_u32_e32 v44, s70, v1
	s_mov_b32 s23, 0x20000
	s_lshl_b32 s22, s82, 9
	v_cmp_gt_i32_e64 s[0:1], s23, v44
	s_and_saveexec_b64 s[2:3], s[0:1]
	s_cbranch_execz .LBB0_185
	s_waitcnt lgkmcnt(0)
	s_lshr_b32 s4, s90, 6
	s_lshl_b32 s26, s93, 3
	s_add_i32 s26, s26, s4
	s_lshl_b32 s27, s82, 3
	v_mov_b32_e32 v4, 0
